# v22 plus: SGPR-base LDS-DMA addressing (no 64-bit VALU address adds) in the branch, bf16 GEMM1 and both out-GEMM K-loops too
# baseline (speedup 1.0000x reference)
.LBB0_230:
	s_add_u32 s28, s0, 0xfff00080
	s_addc_u32 s29, s1, -1
	s_add_i32 s51, 0, 0x10000
	s_cmp_eq_u32 s50, 60
	s_cselect_b32 s31, s34, s29
	s_cselect_b32 s30, s35, s28
	v_add_u32_e32 v0, s51, v179
	s_cselect_b32 s29, s27, s43
	s_cselect_b32 s28, s40, s41
	s_add_i32 s77, 0, 0x14000
	ds_read_b128 v[130:133], v0
	ds_read_b128 v[134:137], v0 offset:1024
	ds_read_b128 v[138:141], v0 offset:2048
	ds_read_b128 v[142:145], v0 offset:3072
	v_add_u32_e32 v0, s77, v179
	ds_read_b128 v[146:149], v0
	ds_read_b128 v[150:153], v0 offset:1024
	ds_read_b128 v[154:157], v0 offset:2048
	ds_read_b128 v[158:161], v0 offset:3072
	s_add_i32 m0, s14, 0xc000
	ds_read_b128 v[174:177], v192
	ds_read_b128 v[180:183], v192 offset:1024
	ds_read_b128 v[184:187], v192 offset:2048
	ds_read_b128 v[188:191], v192 offset:3072
	ds_read_b128 v[200:203], v192 offset:4096
	ds_read_b128 v[204:207], v192 offset:5120
	ds_read_b128 v[208:211], v192 offset:6144
	ds_read_b128 v[212:215], v192 offset:7168
	global_load_lds_dwordx4 v170, s[0:1]
	s_add_i32 m0, s14, 0xe000
	s_nop 0
	global_load_lds_dwordx4 v172, s[0:1]
	s_waitcnt vmcnt(8)
	s_waitcnt lgkmcnt(0)
	s_barrier
	s_waitcnt lgkmcnt(0)
	v_mfma_f32_16x16x32_bf16 v[126:129], v[130:133], v[174:177], v[126:129]
	v_mfma_f32_16x16x32_bf16 v[126:129], v[134:137], v[180:183], v[126:129]
	v_mfma_f32_16x16x32_bf16 v[110:113], v[130:133], v[184:187], v[110:113]
	v_mfma_f32_16x16x32_bf16 v[110:113], v[134:137], v[188:191], v[110:113]
	v_mfma_f32_16x16x32_bf16 v[94:97], v[130:133], v[200:203], v[94:97]
	v_mfma_f32_16x16x32_bf16 v[94:97], v[134:137], v[204:207], v[94:97]
	v_mfma_f32_16x16x32_bf16 v[78:81], v[130:133], v[208:211], v[78:81]
	v_mfma_f32_16x16x32_bf16 v[78:81], v[134:137], v[212:215], v[78:81]
	v_mfma_f32_16x16x32_bf16 v[122:125], v[138:141], v[174:177], v[122:125]
	v_mfma_f32_16x16x32_bf16 v[122:125], v[142:145], v[180:183], v[122:125]
	v_mfma_f32_16x16x32_bf16 v[106:109], v[138:141], v[184:187], v[106:109]
	v_mfma_f32_16x16x32_bf16 v[106:109], v[142:145], v[188:191], v[106:109]
	v_mfma_f32_16x16x32_bf16 v[90:93], v[138:141], v[200:203], v[90:93]
	v_mfma_f32_16x16x32_bf16 v[90:93], v[142:145], v[204:207], v[90:93]
	v_mfma_f32_16x16x32_bf16 v[74:77], v[138:141], v[208:211], v[74:77]
	v_mfma_f32_16x16x32_bf16 v[74:77], v[142:145], v[212:215], v[74:77]
	v_mfma_f32_16x16x32_bf16 v[118:121], v[146:149], v[174:177], v[118:121]
	v_mfma_f32_16x16x32_bf16 v[118:121], v[150:153], v[180:183], v[118:121]
	v_mfma_f32_16x16x32_bf16 v[102:105], v[146:149], v[184:187], v[102:105]
	v_mfma_f32_16x16x32_bf16 v[102:105], v[150:153], v[188:191], v[102:105]
	v_mfma_f32_16x16x32_bf16 v[86:89], v[146:149], v[200:203], v[86:89]
	v_mfma_f32_16x16x32_bf16 v[86:89], v[150:153], v[204:207], v[86:89]
	v_mfma_f32_16x16x32_bf16 v[70:73], v[146:149], v[208:211], v[70:73]
	v_mfma_f32_16x16x32_bf16 v[70:73], v[150:153], v[212:215], v[70:73]
	v_mfma_f32_16x16x32_bf16 v[114:117], v[154:157], v[174:177], v[114:117]
	v_mfma_f32_16x16x32_bf16 v[114:117], v[158:161], v[180:183], v[114:117]
	v_mfma_f32_16x16x32_bf16 v[98:101], v[154:157], v[184:187], v[98:101]
	v_mfma_f32_16x16x32_bf16 v[98:101], v[158:161], v[188:191], v[98:101]
	v_mfma_f32_16x16x32_bf16 v[82:85], v[154:157], v[200:203], v[82:85]
	v_mfma_f32_16x16x32_bf16 v[82:85], v[158:161], v[204:207], v[82:85]
	v_mfma_f32_16x16x32_bf16 v[66:69], v[154:157], v[208:211], v[66:69]
	v_mfma_f32_16x16x32_bf16 v[66:69], v[158:161], v[212:215], v[66:69]
	s_barrier
	s_add_i32 s51, s51, s9
	s_mov_b32 m0, s51
	ds_read_b128 v[174:177], v192 offset:16384
	ds_read_b128 v[180:183], v192 offset:17408
	ds_read_b128 v[184:187], v192 offset:18432
	ds_read_b128 v[188:191], v192 offset:19456
	ds_read_b128 v[200:203], v192 offset:20480
	ds_read_b128 v[204:207], v192 offset:21504
	ds_read_b128 v[208:211], v192 offset:22528
	ds_read_b128 v[212:215], v192 offset:23552
	global_load_lds_dwordx4 v166, s[28:29]
	s_add_i32 m0, s51, 0x2000
	s_add_u32 s80, s28, 0x100000
	s_addc_u32 s81, s29, 0
	s_add_i32 s51, s77, s9
	global_load_lds_dwordx4 v162, s[28:29]
	s_mov_b32 m0, s51
	s_nop 0
	global_load_lds_dwordx4 v166, s[80:81]
	s_add_i32 m0, s51, 0x2000
	s_nop 0
	global_load_lds_dwordx4 v162, s[80:81]
	s_mov_b32 m0, s14
	s_nop 0
	global_load_lds_dwordx4 v168, s[30:31]
	s_mov_b32 m0, s15
	s_nop 0
	global_load_lds_dwordx4 v164, s[30:31]
	s_waitcnt vmcnt(8)
	s_waitcnt lgkmcnt(0)
	s_barrier
	s_waitcnt lgkmcnt(0)
	v_mfma_f32_16x16x32_bf16 v[62:65], v[130:133], v[174:177], v[62:65]
	v_mfma_f32_16x16x32_bf16 v[62:65], v[134:137], v[180:183], v[62:65]
	v_mfma_f32_16x16x32_bf16 v[46:49], v[130:133], v[184:187], v[46:49]
	v_mfma_f32_16x16x32_bf16 v[46:49], v[134:137], v[188:191], v[46:49]
	v_mfma_f32_16x16x32_bf16 v[30:33], v[130:133], v[200:203], v[30:33]
	v_mfma_f32_16x16x32_bf16 v[30:33], v[134:137], v[204:207], v[30:33]
	v_mfma_f32_16x16x32_bf16 v[14:17], v[130:133], v[208:211], v[14:17]
	v_mfma_f32_16x16x32_bf16 v[14:17], v[134:137], v[212:215], v[14:17]
	v_mfma_f32_16x16x32_bf16 v[58:61], v[138:141], v[174:177], v[58:61]
	v_mfma_f32_16x16x32_bf16 v[58:61], v[142:145], v[180:183], v[58:61]
	v_mfma_f32_16x16x32_bf16 v[42:45], v[138:141], v[184:187], v[42:45]
	v_mfma_f32_16x16x32_bf16 v[42:45], v[142:145], v[188:191], v[42:45]
	v_mfma_f32_16x16x32_bf16 v[26:29], v[138:141], v[200:203], v[26:29]
	v_mfma_f32_16x16x32_bf16 v[26:29], v[142:145], v[204:207], v[26:29]
	v_mfma_f32_16x16x32_bf16 v[10:13], v[138:141], v[208:211], v[10:13]
	v_mfma_f32_16x16x32_bf16 v[10:13], v[142:145], v[212:215], v[10:13]
	v_mfma_f32_16x16x32_bf16 v[54:57], v[146:149], v[174:177], v[54:57]
	v_mfma_f32_16x16x32_bf16 v[54:57], v[150:153], v[180:183], v[54:57]
	v_mfma_f32_16x16x32_bf16 v[38:41], v[146:149], v[184:187], v[38:41]
	v_mfma_f32_16x16x32_bf16 v[38:41], v[150:153], v[188:191], v[38:41]
	v_mfma_f32_16x16x32_bf16 v[22:25], v[146:149], v[200:203], v[22:25]
	v_mfma_f32_16x16x32_bf16 v[22:25], v[150:153], v[204:207], v[22:25]
	v_mfma_f32_16x16x32_bf16 v[6:9], v[146:149], v[208:211], v[6:9]
	v_mfma_f32_16x16x32_bf16 v[6:9], v[150:153], v[212:215], v[6:9]
	v_mfma_f32_16x16x32_bf16 v[50:53], v[154:157], v[174:177], v[50:53]
	v_mfma_f32_16x16x32_bf16 v[50:53], v[158:161], v[180:183], v[50:53]
	v_mfma_f32_16x16x32_bf16 v[34:37], v[154:157], v[184:187], v[34:37]
	v_mfma_f32_16x16x32_bf16 v[34:37], v[158:161], v[188:191], v[34:37]
	v_mfma_f32_16x16x32_bf16 v[18:21], v[154:157], v[200:203], v[18:21]
	v_mfma_f32_16x16x32_bf16 v[18:21], v[158:161], v[204:207], v[18:21]
	v_mfma_f32_16x16x32_bf16 v[2:5], v[154:157], v[208:211], v[2:5]
	v_mfma_f32_16x16x32_bf16 v[2:5], v[158:161], v[212:215], v[2:5]
	s_barrier
	s_add_i32 s51, 0, 0x18000
	v_add_u32_e32 v0, s51, v179
	s_add_i32 s77, 0, 0x1c000
	ds_read_b128 v[130:133], v0
	ds_read_b128 v[134:137], v0 offset:1024
	ds_read_b128 v[138:141], v0 offset:2048
	ds_read_b128 v[142:145], v0 offset:3072
	v_add_u32_e32 v0, s77, v179
	ds_read_b128 v[146:149], v0
	ds_read_b128 v[150:153], v0 offset:1024
	ds_read_b128 v[154:157], v0 offset:2048
	ds_read_b128 v[158:161], v0 offset:3072
	s_add_u32 s30, s30, 0x100000
	s_addc_u32 s31, s31, 0
	s_mov_b32 m0, s52
	ds_read_b128 v[174:177], v192 offset:32768
	ds_read_b128 v[180:183], v192 offset:33792
	ds_read_b128 v[184:187], v192 offset:34816
	ds_read_b128 v[188:191], v192 offset:35840
	ds_read_b128 v[200:203], v192 offset:36864
	ds_read_b128 v[204:207], v192 offset:37888
	ds_read_b128 v[208:211], v192 offset:38912
	ds_read_b128 v[212:215], v192 offset:39936
	global_load_lds_dwordx4 v168, s[30:31]
	s_mov_b32 m0, s53
	s_nop 0
	global_load_lds_dwordx4 v164, s[30:31]
	s_waitcnt vmcnt(8)
	s_waitcnt lgkmcnt(0)
	s_barrier
	s_waitcnt lgkmcnt(0)
	v_mfma_f32_16x16x32_bf16 v[126:129], v[130:133], v[174:177], v[126:129]
	v_mfma_f32_16x16x32_bf16 v[126:129], v[134:137], v[180:183], v[126:129]
	v_mfma_f32_16x16x32_bf16 v[110:113], v[130:133], v[184:187], v[110:113]
	v_mfma_f32_16x16x32_bf16 v[110:113], v[134:137], v[188:191], v[110:113]
	v_mfma_f32_16x16x32_bf16 v[94:97], v[130:133], v[200:203], v[94:97]
	v_mfma_f32_16x16x32_bf16 v[94:97], v[134:137], v[204:207], v[94:97]
	v_mfma_f32_16x16x32_bf16 v[78:81], v[130:133], v[208:211], v[78:81]
	v_mfma_f32_16x16x32_bf16 v[78:81], v[134:137], v[212:215], v[78:81]
	v_mfma_f32_16x16x32_bf16 v[122:125], v[138:141], v[174:177], v[122:125]
	v_mfma_f32_16x16x32_bf16 v[122:125], v[142:145], v[180:183], v[122:125]
	v_mfma_f32_16x16x32_bf16 v[106:109], v[138:141], v[184:187], v[106:109]
	v_mfma_f32_16x16x32_bf16 v[106:109], v[142:145], v[188:191], v[106:109]
	v_mfma_f32_16x16x32_bf16 v[90:93], v[138:141], v[200:203], v[90:93]
	v_mfma_f32_16x16x32_bf16 v[90:93], v[142:145], v[204:207], v[90:93]
	v_mfma_f32_16x16x32_bf16 v[74:77], v[138:141], v[208:211], v[74:77]
	v_mfma_f32_16x16x32_bf16 v[74:77], v[142:145], v[212:215], v[74:77]
	v_mfma_f32_16x16x32_bf16 v[118:121], v[146:149], v[174:177], v[118:121]
	v_mfma_f32_16x16x32_bf16 v[118:121], v[150:153], v[180:183], v[118:121]
	v_mfma_f32_16x16x32_bf16 v[102:105], v[146:149], v[184:187], v[102:105]
	v_mfma_f32_16x16x32_bf16 v[102:105], v[150:153], v[188:191], v[102:105]
	v_mfma_f32_16x16x32_bf16 v[86:89], v[146:149], v[200:203], v[86:89]
	v_mfma_f32_16x16x32_bf16 v[86:89], v[150:153], v[204:207], v[86:89]
	v_mfma_f32_16x16x32_bf16 v[70:73], v[146:149], v[208:211], v[70:73]
	v_mfma_f32_16x16x32_bf16 v[70:73], v[150:153], v[212:215], v[70:73]
	v_mfma_f32_16x16x32_bf16 v[114:117], v[154:157], v[174:177], v[114:117]
	v_mfma_f32_16x16x32_bf16 v[114:117], v[158:161], v[180:183], v[114:117]
	v_mfma_f32_16x16x32_bf16 v[98:101], v[154:157], v[184:187], v[98:101]
	v_mfma_f32_16x16x32_bf16 v[98:101], v[158:161], v[188:191], v[98:101]
	v_mfma_f32_16x16x32_bf16 v[82:85], v[154:157], v[200:203], v[82:85]
	v_mfma_f32_16x16x32_bf16 v[82:85], v[158:161], v[204:207], v[82:85]
	v_mfma_f32_16x16x32_bf16 v[66:69], v[154:157], v[208:211], v[66:69]
	v_mfma_f32_16x16x32_bf16 v[66:69], v[158:161], v[212:215], v[66:69]
	s_barrier
	s_add_u32 s100, s30, 0xfff00080
	s_addc_u32 s101, s31, -1
	s_add_u32 s98, s28, 0x80
	s_addc_u32 s99, s29, 0
	s_add_i32 s30, s51, s9
	s_mov_b32 m0, s30
	ds_read_b128 v[174:177], v192 offset:49152
	ds_read_b128 v[180:183], v192 offset:50176
	ds_read_b128 v[184:187], v192 offset:51200
	ds_read_b128 v[188:191], v192 offset:52224
	ds_read_b128 v[200:203], v192 offset:53248
	ds_read_b128 v[204:207], v192 offset:54272
	ds_read_b128 v[208:211], v192 offset:55296
	ds_read_b128 v[212:215], v192 offset:56320
	global_load_lds_dwordx4 v166, s[98:99]
	s_add_i32 m0, s30, 0x2000
	s_add_u32 s28, s28, 0x100080
	s_addc_u32 s29, s29, 0
	s_add_i32 s30, s77, s9
	global_load_lds_dwordx4 v162, s[98:99]
	s_mov_b32 m0, s30
	s_nop 0
	global_load_lds_dwordx4 v166, s[28:29]
	s_add_i32 m0, s30, 0x2000
	s_nop 0
	global_load_lds_dwordx4 v162, s[28:29]
	s_mov_b32 m0, s54
	s_nop 0
	global_load_lds_dwordx4 v168, s[100:101]
	s_mov_b32 m0, s55
	s_nop 0
	global_load_lds_dwordx4 v164, s[100:101]
	s_waitcnt vmcnt(8)
	s_waitcnt lgkmcnt(0)
	s_barrier
	s_waitcnt lgkmcnt(0)
	v_mfma_f32_16x16x32_bf16 v[62:65], v[130:133], v[174:177], v[62:65]
	v_mfma_f32_16x16x32_bf16 v[62:65], v[134:137], v[180:183], v[62:65]
	v_mfma_f32_16x16x32_bf16 v[46:49], v[130:133], v[184:187], v[46:49]
	v_mfma_f32_16x16x32_bf16 v[46:49], v[134:137], v[188:191], v[46:49]
	v_mfma_f32_16x16x32_bf16 v[30:33], v[130:133], v[200:203], v[30:33]
	v_mfma_f32_16x16x32_bf16 v[30:33], v[134:137], v[204:207], v[30:33]
	v_mfma_f32_16x16x32_bf16 v[14:17], v[130:133], v[208:211], v[14:17]
	v_mfma_f32_16x16x32_bf16 v[14:17], v[134:137], v[212:215], v[14:17]
	v_mfma_f32_16x16x32_bf16 v[58:61], v[138:141], v[174:177], v[58:61]
	v_mfma_f32_16x16x32_bf16 v[58:61], v[142:145], v[180:183], v[58:61]
	v_mfma_f32_16x16x32_bf16 v[42:45], v[138:141], v[184:187], v[42:45]
	v_mfma_f32_16x16x32_bf16 v[42:45], v[142:145], v[188:191], v[42:45]
	v_mfma_f32_16x16x32_bf16 v[26:29], v[138:141], v[200:203], v[26:29]
	v_mfma_f32_16x16x32_bf16 v[26:29], v[142:145], v[204:207], v[26:29]
	v_mfma_f32_16x16x32_bf16 v[10:13], v[138:141], v[208:211], v[10:13]
	v_mfma_f32_16x16x32_bf16 v[10:13], v[142:145], v[212:215], v[10:13]
	v_mfma_f32_16x16x32_bf16 v[54:57], v[146:149], v[174:177], v[54:57]
	v_mfma_f32_16x16x32_bf16 v[54:57], v[150:153], v[180:183], v[54:57]
	v_mfma_f32_16x16x32_bf16 v[38:41], v[146:149], v[184:187], v[38:41]
	v_mfma_f32_16x16x32_bf16 v[38:41], v[150:153], v[188:191], v[38:41]
	v_mfma_f32_16x16x32_bf16 v[22:25], v[146:149], v[200:203], v[22:25]
	v_mfma_f32_16x16x32_bf16 v[22:25], v[150:153], v[204:207], v[22:25]
	v_mfma_f32_16x16x32_bf16 v[6:9], v[146:149], v[208:211], v[6:9]
	v_mfma_f32_16x16x32_bf16 v[6:9], v[150:153], v[212:215], v[6:9]
	v_mfma_f32_16x16x32_bf16 v[50:53], v[154:157], v[174:177], v[50:53]
	v_mfma_f32_16x16x32_bf16 v[50:53], v[158:161], v[180:183], v[50:53]
	v_mfma_f32_16x16x32_bf16 v[34:37], v[154:157], v[184:187], v[34:37]
	v_mfma_f32_16x16x32_bf16 v[34:37], v[158:161], v[188:191], v[34:37]
	v_mfma_f32_16x16x32_bf16 v[18:21], v[154:157], v[200:203], v[18:21]
	v_mfma_f32_16x16x32_bf16 v[18:21], v[158:161], v[204:207], v[18:21]
	v_mfma_f32_16x16x32_bf16 v[2:5], v[154:157], v[208:211], v[2:5]
	v_mfma_f32_16x16x32_bf16 v[2:5], v[158:161], v[212:215], v[2:5]
	s_barrier
	s_add_i32 s50, s50, 2
	s_add_u32 s0, s0, 0x100
	s_addc_u32 s1, s1, 0
	s_add_u32 s41, s41, 0x100
	s_addc_u32 s43, s43, 0
	s_cmp_gt_u32 s50, 61
	s_cbranch_scc0 .LBB0_230
	s_and_b64 vcc, exec, s[22:23]
	s_cbranch_vccz .LBB0_233
	s_barrier

.LBB0_577:
	s_add_u32 s34, s30, 0xfff80080
	s_addc_u32 s35, s31, -1
	s_add_i32 s66, 0, 0x10000
	s_cmp_eq_u32 s57, 28
	s_cselect_b32 s43, s19, s35
	s_cselect_b32 s42, s23, s34
	v_add_u32_e32 v0, s66, v228
	s_cselect_b32 s35, s25, s56
	s_cselect_b32 s34, s54, s55
	s_add_i32 s73, 0, 0x14000
	ds_read_b128 v[132:135], v0
	ds_read_b128 v[136:139], v0 offset:1024
	ds_read_b128 v[140:143], v0 offset:2048
	ds_read_b128 v[144:147], v0 offset:3072
	v_add_u32_e32 v0, s73, v228
	ds_read_b128 v[148:151], v0
	ds_read_b128 v[152:155], v0 offset:1024
	ds_read_b128 v[156:159], v0 offset:2048
	ds_read_b128 v[160:163], v0 offset:3072
	s_add_i32 m0, s46, 0xc000
	ds_read_b128 v[164:167], v230
	ds_read_b128 v[168:171], v230 offset:1024
	ds_read_b128 v[172:175], v230 offset:2048
	ds_read_b128 v[176:179], v230 offset:3072
	ds_read_b128 v[180:183], v230 offset:4096
	ds_read_b128 v[184:187], v230 offset:5120
	ds_read_b128 v[188:191], v230 offset:6144
	ds_read_b128 v[192:195], v230 offset:7168
	global_load_lds_dwordx4 v208, s[30:31]
	s_add_i32 m0, s46, 0xe000
	s_nop 0
	global_load_lds_dwordx4 v210, s[30:31]
	s_waitcnt vmcnt(8)
	s_waitcnt lgkmcnt(0)
	s_barrier
	s_waitcnt lgkmcnt(0)
	v_mfma_f32_16x16x32_bf16 v[128:131], v[132:135], v[164:167], v[128:131]
	v_mfma_f32_16x16x32_bf16 v[128:131], v[136:139], v[168:171], v[128:131]
	v_mfma_f32_16x16x32_bf16 v[120:123], v[132:135], v[172:175], v[120:123]
	v_mfma_f32_16x16x32_bf16 v[120:123], v[136:139], v[176:179], v[120:123]
	v_mfma_f32_16x16x32_bf16 v[112:115], v[132:135], v[180:183], v[112:115]
	v_mfma_f32_16x16x32_bf16 v[112:115], v[136:139], v[184:187], v[112:115]
	v_mfma_f32_16x16x32_bf16 v[104:107], v[132:135], v[188:191], v[104:107]
	v_mfma_f32_16x16x32_bf16 v[104:107], v[136:139], v[192:195], v[104:107]
	v_mfma_f32_16x16x32_bf16 v[124:127], v[140:143], v[164:167], v[124:127]
	v_mfma_f32_16x16x32_bf16 v[124:127], v[144:147], v[168:171], v[124:127]
	v_mfma_f32_16x16x32_bf16 v[116:119], v[140:143], v[172:175], v[116:119]
	v_mfma_f32_16x16x32_bf16 v[116:119], v[144:147], v[176:179], v[116:119]
	v_mfma_f32_16x16x32_bf16 v[108:111], v[140:143], v[180:183], v[108:111]
	v_mfma_f32_16x16x32_bf16 v[108:111], v[144:147], v[184:187], v[108:111]
	v_mfma_f32_16x16x32_bf16 v[100:103], v[140:143], v[188:191], v[100:103]
	v_mfma_f32_16x16x32_bf16 v[100:103], v[144:147], v[192:195], v[100:103]
	v_mfma_f32_16x16x32_bf16 v[96:99], v[148:151], v[164:167], v[96:99]
	v_mfma_f32_16x16x32_bf16 v[96:99], v[152:155], v[168:171], v[96:99]
	v_mfma_f32_16x16x32_bf16 v[88:91], v[148:151], v[172:175], v[88:91]
	v_mfma_f32_16x16x32_bf16 v[88:91], v[152:155], v[176:179], v[88:91]
	v_mfma_f32_16x16x32_bf16 v[80:83], v[148:151], v[180:183], v[80:83]
	v_mfma_f32_16x16x32_bf16 v[80:83], v[152:155], v[184:187], v[80:83]
	v_mfma_f32_16x16x32_bf16 v[72:75], v[148:151], v[188:191], v[72:75]
	v_mfma_f32_16x16x32_bf16 v[72:75], v[152:155], v[192:195], v[72:75]
	v_mfma_f32_16x16x32_bf16 v[92:95], v[156:159], v[164:167], v[92:95]
	v_mfma_f32_16x16x32_bf16 v[92:95], v[160:163], v[168:171], v[92:95]
	v_mfma_f32_16x16x32_bf16 v[84:87], v[156:159], v[172:175], v[84:87]
	v_mfma_f32_16x16x32_bf16 v[84:87], v[160:163], v[176:179], v[84:87]
	v_mfma_f32_16x16x32_bf16 v[76:79], v[156:159], v[180:183], v[76:79]
	v_mfma_f32_16x16x32_bf16 v[76:79], v[160:163], v[184:187], v[76:79]
	v_mfma_f32_16x16x32_bf16 v[68:71], v[156:159], v[188:191], v[68:71]
	v_mfma_f32_16x16x32_bf16 v[68:71], v[160:163], v[192:195], v[68:71]
	s_barrier
	s_add_i32 s66, s66, s15
	s_mov_b32 m0, s66
	ds_read_b128 v[164:167], v230 offset:16384
	ds_read_b128 v[168:171], v230 offset:17408
	ds_read_b128 v[172:175], v230 offset:18432
	ds_read_b128 v[176:179], v230 offset:19456
	ds_read_b128 v[180:183], v230 offset:20480
	ds_read_b128 v[184:187], v230 offset:21504
	ds_read_b128 v[188:191], v230 offset:22528
	ds_read_b128 v[192:195], v230 offset:23552
	global_load_lds_dwordx4 v204, s[34:35]
	s_add_i32 m0, s66, 0x2000
	s_add_u32 s66, s34, 0x80000
	s_addc_u32 s67, s35, 0
	s_add_i32 s73, s73, s15
	global_load_lds_dwordx4 v200, s[34:35]
	s_mov_b32 m0, s73
	s_nop 0
	global_load_lds_dwordx4 v204, s[66:67]
	s_add_i32 m0, s73, 0x2000
	s_nop 0
	global_load_lds_dwordx4 v200, s[66:67]
	s_mov_b32 m0, s46
	s_nop 0
	global_load_lds_dwordx4 v206, s[42:43]
	s_mov_b32 m0, s47
	s_nop 0
	global_load_lds_dwordx4 v202, s[42:43]
	s_waitcnt vmcnt(8)
	s_waitcnt lgkmcnt(0)
	s_barrier
	s_waitcnt lgkmcnt(0)
	v_mfma_f32_16x16x32_bf16 v[64:67], v[132:135], v[164:167], v[64:67]
	v_mfma_f32_16x16x32_bf16 v[64:67], v[136:139], v[168:171], v[64:67]
	v_mfma_f32_16x16x32_bf16 v[56:59], v[132:135], v[172:175], v[56:59]
	v_mfma_f32_16x16x32_bf16 v[56:59], v[136:139], v[176:179], v[56:59]
	v_mfma_f32_16x16x32_bf16 v[48:51], v[132:135], v[180:183], v[48:51]
	v_mfma_f32_16x16x32_bf16 v[48:51], v[136:139], v[184:187], v[48:51]
	v_mfma_f32_16x16x32_bf16 v[40:43], v[132:135], v[188:191], v[40:43]
	v_mfma_f32_16x16x32_bf16 v[40:43], v[136:139], v[192:195], v[40:43]
	v_mfma_f32_16x16x32_bf16 v[60:63], v[140:143], v[164:167], v[60:63]
	v_mfma_f32_16x16x32_bf16 v[60:63], v[144:147], v[168:171], v[60:63]
	v_mfma_f32_16x16x32_bf16 v[52:55], v[140:143], v[172:175], v[52:55]
	v_mfma_f32_16x16x32_bf16 v[52:55], v[144:147], v[176:179], v[52:55]
	v_mfma_f32_16x16x32_bf16 v[44:47], v[140:143], v[180:183], v[44:47]
	v_mfma_f32_16x16x32_bf16 v[44:47], v[144:147], v[184:187], v[44:47]
	v_mfma_f32_16x16x32_bf16 v[36:39], v[140:143], v[188:191], v[36:39]
	v_mfma_f32_16x16x32_bf16 v[36:39], v[144:147], v[192:195], v[36:39]
	v_mfma_f32_16x16x32_bf16 v[32:35], v[148:151], v[164:167], v[32:35]
	v_mfma_f32_16x16x32_bf16 v[32:35], v[152:155], v[168:171], v[32:35]
	v_mfma_f32_16x16x32_bf16 v[28:31], v[156:159], v[164:167], v[28:31]
	v_mfma_f32_16x16x32_bf16 v[28:31], v[160:163], v[168:171], v[28:31]
	v_mfma_f32_16x16x32_bf16 v[24:27], v[148:151], v[172:175], v[24:27]
	v_mfma_f32_16x16x32_bf16 v[24:27], v[152:155], v[176:179], v[24:27]
	v_mfma_f32_16x16x32_bf16 v[20:23], v[156:159], v[172:175], v[20:23]
	v_mfma_f32_16x16x32_bf16 v[20:23], v[160:163], v[176:179], v[20:23]
	v_mfma_f32_16x16x32_bf16 v[16:19], v[148:151], v[180:183], v[16:19]
	v_mfma_f32_16x16x32_bf16 v[16:19], v[152:155], v[184:187], v[16:19]
	v_mfma_f32_16x16x32_bf16 v[12:15], v[156:159], v[180:183], v[12:15]
	v_mfma_f32_16x16x32_bf16 v[12:15], v[160:163], v[184:187], v[12:15]
	v_mfma_f32_16x16x32_bf16 v[8:11], v[148:151], v[188:191], v[8:11]
	v_mfma_f32_16x16x32_bf16 v[8:11], v[152:155], v[192:195], v[8:11]
	v_mfma_f32_16x16x32_bf16 v[2:5], v[156:159], v[188:191], v[4:7]
	v_mfma_f32_16x16x32_bf16 v[2:5], v[160:163], v[192:195], v[2:5]
	s_barrier
	s_add_i32 s66, 0, 0x18000
	v_add_u32_e32 v0, s66, v228
	s_add_i32 s67, 0, 0x1c000
	ds_read_b128 v[132:135], v0
	ds_read_b128 v[136:139], v0 offset:1024
	ds_read_b128 v[140:143], v0 offset:2048
	ds_read_b128 v[144:147], v0 offset:3072
	v_add_u32_e32 v0, s67, v228
	ds_read_b128 v[148:151], v0
	ds_read_b128 v[152:155], v0 offset:1024
	ds_read_b128 v[156:159], v0 offset:2048
	ds_read_b128 v[160:163], v0 offset:3072
	s_add_u32 s42, s42, 0x80000
	s_addc_u32 s43, s43, 0
	s_mov_b32 m0, s48
	ds_read_b128 v[164:167], v230 offset:32768
	ds_read_b128 v[168:171], v230 offset:33792
	ds_read_b128 v[172:175], v230 offset:34816
	ds_read_b128 v[176:179], v230 offset:35840
	ds_read_b128 v[180:183], v230 offset:36864
	ds_read_b128 v[184:187], v230 offset:37888
	ds_read_b128 v[188:191], v230 offset:38912
	ds_read_b128 v[192:195], v230 offset:39936
	global_load_lds_dwordx4 v206, s[42:43]
	s_mov_b32 m0, s49
	s_nop 0
	global_load_lds_dwordx4 v202, s[42:43]
	s_waitcnt vmcnt(8)
	s_waitcnt lgkmcnt(0)
	s_barrier
	s_waitcnt lgkmcnt(0)
	v_mfma_f32_16x16x32_bf16 v[128:131], v[132:135], v[164:167], v[128:131]
	v_mfma_f32_16x16x32_bf16 v[128:131], v[136:139], v[168:171], v[128:131]
	v_mfma_f32_16x16x32_bf16 v[120:123], v[132:135], v[172:175], v[120:123]
	v_mfma_f32_16x16x32_bf16 v[120:123], v[136:139], v[176:179], v[120:123]
	v_mfma_f32_16x16x32_bf16 v[112:115], v[132:135], v[180:183], v[112:115]
	v_mfma_f32_16x16x32_bf16 v[112:115], v[136:139], v[184:187], v[112:115]
	v_mfma_f32_16x16x32_bf16 v[104:107], v[132:135], v[188:191], v[104:107]
	v_mfma_f32_16x16x32_bf16 v[104:107], v[136:139], v[192:195], v[104:107]
	v_mfma_f32_16x16x32_bf16 v[124:127], v[140:143], v[164:167], v[124:127]
	v_mfma_f32_16x16x32_bf16 v[124:127], v[144:147], v[168:171], v[124:127]
	v_mfma_f32_16x16x32_bf16 v[116:119], v[140:143], v[172:175], v[116:119]
	v_mfma_f32_16x16x32_bf16 v[116:119], v[144:147], v[176:179], v[116:119]
	v_mfma_f32_16x16x32_bf16 v[108:111], v[140:143], v[180:183], v[108:111]
	v_mfma_f32_16x16x32_bf16 v[108:111], v[144:147], v[184:187], v[108:111]
	v_mfma_f32_16x16x32_bf16 v[100:103], v[140:143], v[188:191], v[100:103]
	v_mfma_f32_16x16x32_bf16 v[100:103], v[144:147], v[192:195], v[100:103]
	v_mfma_f32_16x16x32_bf16 v[96:99], v[148:151], v[164:167], v[96:99]
	v_mfma_f32_16x16x32_bf16 v[96:99], v[152:155], v[168:171], v[96:99]
	v_mfma_f32_16x16x32_bf16 v[88:91], v[148:151], v[172:175], v[88:91]
	v_mfma_f32_16x16x32_bf16 v[88:91], v[152:155], v[176:179], v[88:91]
	v_mfma_f32_16x16x32_bf16 v[80:83], v[148:151], v[180:183], v[80:83]
	v_mfma_f32_16x16x32_bf16 v[80:83], v[152:155], v[184:187], v[80:83]
	v_mfma_f32_16x16x32_bf16 v[72:75], v[148:151], v[188:191], v[72:75]
	v_mfma_f32_16x16x32_bf16 v[72:75], v[152:155], v[192:195], v[72:75]
	v_mfma_f32_16x16x32_bf16 v[92:95], v[156:159], v[164:167], v[92:95]
	v_mfma_f32_16x16x32_bf16 v[92:95], v[160:163], v[168:171], v[92:95]
	v_mfma_f32_16x16x32_bf16 v[84:87], v[156:159], v[172:175], v[84:87]
	v_mfma_f32_16x16x32_bf16 v[84:87], v[160:163], v[176:179], v[84:87]
	v_mfma_f32_16x16x32_bf16 v[76:79], v[156:159], v[180:183], v[76:79]
	v_mfma_f32_16x16x32_bf16 v[76:79], v[160:163], v[184:187], v[76:79]
	v_mfma_f32_16x16x32_bf16 v[68:71], v[156:159], v[188:191], v[68:71]
	v_mfma_f32_16x16x32_bf16 v[68:71], v[160:163], v[192:195], v[68:71]
	s_barrier
	s_add_u32 s100, s42, 0xfff80080
	s_addc_u32 s101, s43, -1
	s_add_i32 s42, s66, s15
	s_add_u32 s98, s34, 0x80
	s_addc_u32 s99, s35, 0
	s_mov_b32 m0, s42
	ds_read_b128 v[164:167], v230 offset:49152
	ds_read_b128 v[168:171], v230 offset:50176
	ds_read_b128 v[172:175], v230 offset:51200
	ds_read_b128 v[176:179], v230 offset:52224
	ds_read_b128 v[180:183], v230 offset:53248
	ds_read_b128 v[184:187], v230 offset:54272
	ds_read_b128 v[188:191], v230 offset:55296
	ds_read_b128 v[192:195], v230 offset:56320
	global_load_lds_dwordx4 v204, s[98:99]
	s_add_i32 m0, s42, 0x2000
	s_add_u32 s34, s34, 0x80080
	s_addc_u32 s35, s35, 0
	s_add_i32 s42, s67, s15
	global_load_lds_dwordx4 v200, s[98:99]
	s_mov_b32 m0, s42
	s_nop 0
	global_load_lds_dwordx4 v204, s[34:35]
	s_add_i32 m0, s42, 0x2000
	s_nop 0
	global_load_lds_dwordx4 v200, s[34:35]
	s_mov_b32 m0, s50
	s_nop 0
	global_load_lds_dwordx4 v206, s[100:101]
	s_mov_b32 m0, s51
	s_nop 0
	global_load_lds_dwordx4 v202, s[100:101]
	s_waitcnt vmcnt(8)
	s_waitcnt lgkmcnt(0)
	s_barrier
	s_waitcnt lgkmcnt(0)
	v_mfma_f32_16x16x32_bf16 v[64:67], v[132:135], v[164:167], v[64:67]
	v_mfma_f32_16x16x32_bf16 v[64:67], v[136:139], v[168:171], v[64:67]
	v_mfma_f32_16x16x32_bf16 v[56:59], v[132:135], v[172:175], v[56:59]
	v_mfma_f32_16x16x32_bf16 v[56:59], v[136:139], v[176:179], v[56:59]
	v_mfma_f32_16x16x32_bf16 v[48:51], v[132:135], v[180:183], v[48:51]
	v_mfma_f32_16x16x32_bf16 v[48:51], v[136:139], v[184:187], v[48:51]
	v_mfma_f32_16x16x32_bf16 v[40:43], v[132:135], v[188:191], v[40:43]
	v_mfma_f32_16x16x32_bf16 v[40:43], v[136:139], v[192:195], v[40:43]
	v_mfma_f32_16x16x32_bf16 v[60:63], v[140:143], v[164:167], v[60:63]
	v_mfma_f32_16x16x32_bf16 v[60:63], v[144:147], v[168:171], v[60:63]
	v_mfma_f32_16x16x32_bf16 v[52:55], v[140:143], v[172:175], v[52:55]
	v_mfma_f32_16x16x32_bf16 v[52:55], v[144:147], v[176:179], v[52:55]
	v_mfma_f32_16x16x32_bf16 v[44:47], v[140:143], v[180:183], v[44:47]
	v_mfma_f32_16x16x32_bf16 v[44:47], v[144:147], v[184:187], v[44:47]
	v_mfma_f32_16x16x32_bf16 v[36:39], v[140:143], v[188:191], v[36:39]
	v_mfma_f32_16x16x32_bf16 v[36:39], v[144:147], v[192:195], v[36:39]
	v_mfma_f32_16x16x32_bf16 v[32:35], v[148:151], v[164:167], v[32:35]
	v_mfma_f32_16x16x32_bf16 v[32:35], v[152:155], v[168:171], v[32:35]
	v_mfma_f32_16x16x32_bf16 v[28:31], v[156:159], v[164:167], v[28:31]
	v_mfma_f32_16x16x32_bf16 v[28:31], v[160:163], v[168:171], v[28:31]
	v_mfma_f32_16x16x32_bf16 v[24:27], v[148:151], v[172:175], v[24:27]
	v_mfma_f32_16x16x32_bf16 v[24:27], v[152:155], v[176:179], v[24:27]
	v_mfma_f32_16x16x32_bf16 v[20:23], v[156:159], v[172:175], v[20:23]
	v_mfma_f32_16x16x32_bf16 v[20:23], v[160:163], v[176:179], v[20:23]
	v_mfma_f32_16x16x32_bf16 v[16:19], v[148:151], v[180:183], v[16:19]
	v_mfma_f32_16x16x32_bf16 v[16:19], v[152:155], v[184:187], v[16:19]
	v_mfma_f32_16x16x32_bf16 v[12:15], v[156:159], v[180:183], v[12:15]
	v_mfma_f32_16x16x32_bf16 v[12:15], v[160:163], v[184:187], v[12:15]
	v_mfma_f32_16x16x32_bf16 v[6:9], v[148:151], v[188:191], v[8:11]
	v_mfma_f32_16x16x32_bf16 v[8:11], v[152:155], v[192:195], v[6:9]
	v_mfma_f32_16x16x32_bf16 v[2:5], v[156:159], v[188:191], v[2:5]
	v_mfma_f32_16x16x32_bf16 v[4:7], v[160:163], v[192:195], v[2:5]
	s_barrier
	s_add_i32 s57, s57, 2
	s_add_u32 s30, s30, 0x100
	s_addc_u32 s31, s31, 0
	s_add_u32 s55, s55, 0x100
	s_addc_u32 s56, s56, 0
	s_cmp_gt_u32 s57, 29
	s_cbranch_scc0 .LBB0_577
	s_and_b64 vcc, exec, s[20:21]
	s_cbranch_vccz .LBB0_580
	s_barrier

.LBB0_779:
	s_add_u32 s34, s30, 0xfff80080
	s_addc_u32 s35, s31, -1
	s_add_i32 s66, 0, 0x10000
	s_cmp_eq_u32 s57, 28
	s_cselect_b32 s43, s25, s35
	s_cselect_b32 s42, s53, s34
	s_cselect_b32 s35, s23, s56
	s_cselect_b32 s34, s54, s55
	s_add_i32 s73, 0, 0x14000
	v_add_u32_e32 v114, s66, v157
	v_add_u32_e32 v156, s73, v157
	ds_read_b128 v[90:93], v114
	ds_read_b128 v[94:97], v114 offset:1024
	ds_read_b128 v[106:109], v114 offset:2048
	ds_read_b128 v[114:117], v114 offset:3072
	ds_read_b128 v[162:165], v156
	ds_read_b128 v[166:169], v156 offset:1024
	ds_read_b128 v[170:173], v156 offset:2048
	ds_read_b128 v[174:177], v156 offset:3072
	s_add_i32 m0, s14, 0xc000
	ds_read_b128 v[178:181], v161
	ds_read_b128 v[182:185], v161 offset:1024
	ds_read_b128 v[186:189], v161 offset:2048
	ds_read_b128 v[190:193], v161 offset:3072
	ds_read_b128 v[200:203], v161 offset:4096
	ds_read_b128 v[204:207], v161 offset:5120
	ds_read_b128 v[208:211], v161 offset:6144
	ds_read_b128 v[212:215], v161 offset:7168
	global_load_lds_dwordx4 v152, s[30:31]
	s_add_i32 m0, s14, 0xe000
	s_nop 0
	global_load_lds_dwordx4 v154, s[30:31]
	s_waitcnt vmcnt(8)
	s_waitcnt lgkmcnt(0)
	s_barrier
	s_waitcnt lgkmcnt(0)
	v_mfma_i32_16x16x64_i8 v[142:145], v[90:93], v[178:181], v[142:145]
	v_mfma_i32_16x16x64_i8 v[142:145], v[94:97], v[182:185], v[142:145]
	v_mfma_i32_16x16x64_i8 v[126:129], v[90:93], v[186:189], v[126:129]
	v_mfma_i32_16x16x64_i8 v[126:129], v[94:97], v[190:193], v[126:129]
	v_mfma_i32_16x16x64_i8 v[102:105], v[90:93], v[200:203], v[102:105]
	v_mfma_i32_16x16x64_i8 v[102:105], v[94:97], v[204:207], v[102:105]
	v_mfma_i32_16x16x64_i8 v[78:81], v[90:93], v[208:211], v[78:81]
	v_mfma_i32_16x16x64_i8 v[78:81], v[94:97], v[212:215], v[78:81]
	v_mfma_i32_16x16x64_i8 v[138:141], v[106:109], v[178:181], v[138:141]
	v_mfma_i32_16x16x64_i8 v[138:141], v[114:117], v[182:185], v[138:141]
	v_mfma_i32_16x16x64_i8 v[122:125], v[106:109], v[186:189], v[122:125]
	v_mfma_i32_16x16x64_i8 v[122:125], v[114:117], v[190:193], v[122:125]
	v_mfma_i32_16x16x64_i8 v[98:101], v[106:109], v[200:203], v[98:101]
	v_mfma_i32_16x16x64_i8 v[98:101], v[114:117], v[204:207], v[98:101]
	v_mfma_i32_16x16x64_i8 v[74:77], v[106:109], v[208:211], v[74:77]
	v_mfma_i32_16x16x64_i8 v[74:77], v[114:117], v[212:215], v[74:77]
	v_mfma_i32_16x16x64_i8 v[134:137], v[162:165], v[178:181], v[134:137]
	v_mfma_i32_16x16x64_i8 v[134:137], v[166:169], v[182:185], v[134:137]
	v_mfma_i32_16x16x64_i8 v[118:121], v[162:165], v[186:189], v[118:121]
	v_mfma_i32_16x16x64_i8 v[118:121], v[166:169], v[190:193], v[118:121]
	v_mfma_i32_16x16x64_i8 v[86:89], v[162:165], v[200:203], v[86:89]
	v_mfma_i32_16x16x64_i8 v[86:89], v[166:169], v[204:207], v[86:89]
	v_mfma_i32_16x16x64_i8 v[70:73], v[162:165], v[208:211], v[70:73]
	v_mfma_i32_16x16x64_i8 v[70:73], v[166:169], v[212:215], v[70:73]
	v_mfma_i32_16x16x64_i8 v[130:133], v[170:173], v[178:181], v[130:133]
	v_mfma_i32_16x16x64_i8 v[130:133], v[174:177], v[182:185], v[130:133]
	v_mfma_i32_16x16x64_i8 v[110:113], v[170:173], v[186:189], v[110:113]
	v_mfma_i32_16x16x64_i8 v[110:113], v[174:177], v[190:193], v[110:113]
	v_mfma_i32_16x16x64_i8 v[82:85], v[170:173], v[200:203], v[82:85]
	v_mfma_i32_16x16x64_i8 v[82:85], v[174:177], v[204:207], v[82:85]
	v_mfma_i32_16x16x64_i8 v[66:69], v[170:173], v[208:211], v[66:69]
	v_mfma_i32_16x16x64_i8 v[66:69], v[174:177], v[212:215], v[66:69]
	s_barrier
	s_add_i32 s66, s66, s9
	s_mov_b32 m0, s66
	ds_read_b128 v[178:181], v161 offset:16384
	ds_read_b128 v[182:185], v161 offset:17408
	ds_read_b128 v[186:189], v161 offset:18432
	ds_read_b128 v[190:193], v161 offset:19456
	ds_read_b128 v[200:203], v161 offset:20480
	ds_read_b128 v[204:207], v161 offset:21504
	ds_read_b128 v[208:211], v161 offset:22528
	ds_read_b128 v[212:215], v161 offset:23552
	global_load_lds_dwordx4 v0, s[34:35]
	s_add_i32 m0, s66, 0x2000
	s_add_u32 s66, s34, 0x80000
	s_addc_u32 s67, s35, 0
	s_add_i32 s73, s73, s9
	global_load_lds_dwordx4 v146, s[34:35]
	s_mov_b32 m0, s73
	s_nop 0
	global_load_lds_dwordx4 v0, s[66:67]
	s_add_i32 m0, s73, 0x2000
	s_nop 0
	global_load_lds_dwordx4 v146, s[66:67]
	s_mov_b32 m0, s14
	s_nop 0
	global_load_lds_dwordx4 v150, s[42:43]
	s_mov_b32 m0, s15
	s_nop 0
	global_load_lds_dwordx4 v148, s[42:43]
	s_waitcnt vmcnt(8)
	s_waitcnt lgkmcnt(0)
	s_barrier
	s_waitcnt lgkmcnt(0)
	v_mfma_i32_16x16x64_i8 v[62:65], v[90:93], v[178:181], v[62:65]
	v_mfma_i32_16x16x64_i8 v[62:65], v[94:97], v[182:185], v[62:65]
	v_mfma_i32_16x16x64_i8 v[46:49], v[90:93], v[186:189], v[46:49]
	v_mfma_i32_16x16x64_i8 v[46:49], v[94:97], v[190:193], v[46:49]
	v_mfma_i32_16x16x64_i8 v[30:33], v[90:93], v[200:203], v[30:33]
	v_mfma_i32_16x16x64_i8 v[30:33], v[94:97], v[204:207], v[30:33]
	v_mfma_i32_16x16x64_i8 v[14:17], v[90:93], v[208:211], v[14:17]
	v_mfma_i32_16x16x64_i8 v[14:17], v[94:97], v[212:215], v[14:17]
	v_mfma_i32_16x16x64_i8 v[58:61], v[106:109], v[178:181], v[58:61]
	v_mfma_i32_16x16x64_i8 v[58:61], v[114:117], v[182:185], v[58:61]
	v_mfma_i32_16x16x64_i8 v[42:45], v[106:109], v[186:189], v[42:45]
	v_mfma_i32_16x16x64_i8 v[42:45], v[114:117], v[190:193], v[42:45]
	v_mfma_i32_16x16x64_i8 v[26:29], v[106:109], v[200:203], v[26:29]
	v_mfma_i32_16x16x64_i8 v[26:29], v[114:117], v[204:207], v[26:29]
	v_mfma_i32_16x16x64_i8 v[10:13], v[106:109], v[208:211], v[10:13]
	v_mfma_i32_16x16x64_i8 v[10:13], v[114:117], v[212:215], v[10:13]
	v_mfma_i32_16x16x64_i8 v[54:57], v[162:165], v[178:181], v[54:57]
	v_mfma_i32_16x16x64_i8 v[54:57], v[166:169], v[182:185], v[54:57]
	v_mfma_i32_16x16x64_i8 v[38:41], v[162:165], v[186:189], v[38:41]
	v_mfma_i32_16x16x64_i8 v[38:41], v[166:169], v[190:193], v[38:41]
	v_mfma_i32_16x16x64_i8 v[22:25], v[162:165], v[200:203], v[22:25]
	v_mfma_i32_16x16x64_i8 v[22:25], v[166:169], v[204:207], v[22:25]
	v_mfma_i32_16x16x64_i8 v[6:9], v[162:165], v[208:211], v[6:9]
	v_mfma_i32_16x16x64_i8 v[6:9], v[166:169], v[212:215], v[6:9]
	v_mfma_i32_16x16x64_i8 v[50:53], v[170:173], v[178:181], v[50:53]
	v_mfma_i32_16x16x64_i8 v[50:53], v[174:177], v[182:185], v[50:53]
	v_mfma_i32_16x16x64_i8 v[34:37], v[170:173], v[186:189], v[34:37]
	v_mfma_i32_16x16x64_i8 v[34:37], v[174:177], v[190:193], v[34:37]
	v_mfma_i32_16x16x64_i8 v[18:21], v[170:173], v[200:203], v[18:21]
	v_mfma_i32_16x16x64_i8 v[18:21], v[174:177], v[204:207], v[18:21]
	v_mfma_i32_16x16x64_i8 v[2:5], v[170:173], v[208:211], v[2:5]
	v_mfma_i32_16x16x64_i8 v[2:5], v[174:177], v[212:215], v[2:5]
	s_barrier
	s_add_i32 s66, 0, 0x18000
	s_add_i32 s67, 0, 0x1c000
	v_add_u32_e32 v114, s66, v157
	v_add_u32_e32 v156, s67, v157
	ds_read_b128 v[90:93], v114
	ds_read_b128 v[94:97], v114 offset:1024
	ds_read_b128 v[106:109], v114 offset:2048
	ds_read_b128 v[114:117], v114 offset:3072
	ds_read_b128 v[162:165], v156
	ds_read_b128 v[166:169], v156 offset:1024
	ds_read_b128 v[170:173], v156 offset:2048
	ds_read_b128 v[174:177], v156 offset:3072
	s_add_u32 s42, s42, 0x80000
	s_addc_u32 s43, s43, 0
	s_mov_b32 m0, s46
	ds_read_b128 v[178:181], v161 offset:32768
	ds_read_b128 v[182:185], v161 offset:33792
	ds_read_b128 v[186:189], v161 offset:34816
	ds_read_b128 v[190:193], v161 offset:35840
	ds_read_b128 v[200:203], v161 offset:36864
	ds_read_b128 v[204:207], v161 offset:37888
	ds_read_b128 v[208:211], v161 offset:38912
	ds_read_b128 v[212:215], v161 offset:39936
	global_load_lds_dwordx4 v150, s[42:43]
	s_mov_b32 m0, s47
	s_nop 0
	global_load_lds_dwordx4 v148, s[42:43]
	s_waitcnt vmcnt(8)
	s_waitcnt lgkmcnt(0)
	s_barrier
	s_waitcnt lgkmcnt(0)
	v_mfma_i32_16x16x64_i8 v[142:145], v[90:93], v[178:181], v[142:145]
	v_mfma_i32_16x16x64_i8 v[142:145], v[94:97], v[182:185], v[142:145]
	v_mfma_i32_16x16x64_i8 v[126:129], v[90:93], v[186:189], v[126:129]
	v_mfma_i32_16x16x64_i8 v[126:129], v[94:97], v[190:193], v[126:129]
	v_mfma_i32_16x16x64_i8 v[102:105], v[90:93], v[200:203], v[102:105]
	v_mfma_i32_16x16x64_i8 v[102:105], v[94:97], v[204:207], v[102:105]
	v_mfma_i32_16x16x64_i8 v[78:81], v[90:93], v[208:211], v[78:81]
	v_mfma_i32_16x16x64_i8 v[78:81], v[94:97], v[212:215], v[78:81]
	v_mfma_i32_16x16x64_i8 v[138:141], v[106:109], v[178:181], v[138:141]
	v_mfma_i32_16x16x64_i8 v[138:141], v[114:117], v[182:185], v[138:141]
	v_mfma_i32_16x16x64_i8 v[122:125], v[106:109], v[186:189], v[122:125]
	v_mfma_i32_16x16x64_i8 v[122:125], v[114:117], v[190:193], v[122:125]
	v_mfma_i32_16x16x64_i8 v[98:101], v[106:109], v[200:203], v[98:101]
	v_mfma_i32_16x16x64_i8 v[98:101], v[114:117], v[204:207], v[98:101]
	v_mfma_i32_16x16x64_i8 v[74:77], v[106:109], v[208:211], v[74:77]
	v_mfma_i32_16x16x64_i8 v[74:77], v[114:117], v[212:215], v[74:77]
	v_mfma_i32_16x16x64_i8 v[134:137], v[162:165], v[178:181], v[134:137]
	v_mfma_i32_16x16x64_i8 v[134:137], v[166:169], v[182:185], v[134:137]
	v_mfma_i32_16x16x64_i8 v[118:121], v[162:165], v[186:189], v[118:121]
	v_mfma_i32_16x16x64_i8 v[118:121], v[166:169], v[190:193], v[118:121]
	v_mfma_i32_16x16x64_i8 v[86:89], v[162:165], v[200:203], v[86:89]
	v_mfma_i32_16x16x64_i8 v[86:89], v[166:169], v[204:207], v[86:89]
	v_mfma_i32_16x16x64_i8 v[70:73], v[162:165], v[208:211], v[70:73]
	v_mfma_i32_16x16x64_i8 v[70:73], v[166:169], v[212:215], v[70:73]
	v_mfma_i32_16x16x64_i8 v[130:133], v[170:173], v[178:181], v[130:133]
	v_mfma_i32_16x16x64_i8 v[130:133], v[174:177], v[182:185], v[130:133]
	v_mfma_i32_16x16x64_i8 v[110:113], v[170:173], v[186:189], v[110:113]
	v_mfma_i32_16x16x64_i8 v[110:113], v[174:177], v[190:193], v[110:113]
	v_mfma_i32_16x16x64_i8 v[82:85], v[170:173], v[200:203], v[82:85]
	v_mfma_i32_16x16x64_i8 v[82:85], v[174:177], v[204:207], v[82:85]
	v_mfma_i32_16x16x64_i8 v[66:69], v[170:173], v[208:211], v[66:69]
	v_mfma_i32_16x16x64_i8 v[66:69], v[174:177], v[212:215], v[66:69]
	s_barrier
	s_add_u32 s100, s42, 0xfff80080
	s_addc_u32 s101, s43, -1
	s_add_u32 s98, s34, 0x80
	s_addc_u32 s99, s35, 0
	s_add_i32 s42, s66, s9
	s_mov_b32 m0, s42
	ds_read_b128 v[178:181], v161 offset:49152
	ds_read_b128 v[182:185], v161 offset:50176
	ds_read_b128 v[186:189], v161 offset:51200
	ds_read_b128 v[190:193], v161 offset:52224
	ds_read_b128 v[200:203], v161 offset:53248
	ds_read_b128 v[204:207], v161 offset:54272
	ds_read_b128 v[208:211], v161 offset:55296
	ds_read_b128 v[212:215], v161 offset:56320
	global_load_lds_dwordx4 v0, s[98:99]
	s_add_i32 m0, s42, 0x2000
	s_add_u32 s34, s34, 0x80080
	s_addc_u32 s35, s35, 0
	s_add_i32 s42, s67, s9
	global_load_lds_dwordx4 v146, s[98:99]
	s_mov_b32 m0, s42
	s_nop 0
	global_load_lds_dwordx4 v0, s[34:35]
	s_add_i32 m0, s42, 0x2000
	s_nop 0
	global_load_lds_dwordx4 v146, s[34:35]
	s_mov_b32 m0, s50
	s_nop 0
	global_load_lds_dwordx4 v150, s[100:101]
	s_mov_b32 m0, s51
	s_nop 0
	global_load_lds_dwordx4 v148, s[100:101]
	s_waitcnt vmcnt(8)
	s_waitcnt lgkmcnt(0)
	s_barrier
	s_waitcnt lgkmcnt(0)
	v_mfma_i32_16x16x64_i8 v[62:65], v[90:93], v[178:181], v[62:65]
	v_mfma_i32_16x16x64_i8 v[62:65], v[94:97], v[182:185], v[62:65]
	v_mfma_i32_16x16x64_i8 v[46:49], v[90:93], v[186:189], v[46:49]
	v_mfma_i32_16x16x64_i8 v[46:49], v[94:97], v[190:193], v[46:49]
	v_mfma_i32_16x16x64_i8 v[30:33], v[90:93], v[200:203], v[30:33]
	v_mfma_i32_16x16x64_i8 v[30:33], v[94:97], v[204:207], v[30:33]
	v_mfma_i32_16x16x64_i8 v[14:17], v[90:93], v[208:211], v[14:17]
	v_mfma_i32_16x16x64_i8 v[14:17], v[94:97], v[212:215], v[14:17]
	v_mfma_i32_16x16x64_i8 v[58:61], v[106:109], v[178:181], v[58:61]
	v_mfma_i32_16x16x64_i8 v[58:61], v[114:117], v[182:185], v[58:61]
	v_mfma_i32_16x16x64_i8 v[42:45], v[106:109], v[186:189], v[42:45]
	v_mfma_i32_16x16x64_i8 v[42:45], v[114:117], v[190:193], v[42:45]
	v_mfma_i32_16x16x64_i8 v[26:29], v[106:109], v[200:203], v[26:29]
	v_mfma_i32_16x16x64_i8 v[26:29], v[114:117], v[204:207], v[26:29]
	v_mfma_i32_16x16x64_i8 v[10:13], v[106:109], v[208:211], v[10:13]
	v_mfma_i32_16x16x64_i8 v[10:13], v[114:117], v[212:215], v[10:13]
	v_mfma_i32_16x16x64_i8 v[54:57], v[162:165], v[178:181], v[54:57]
	v_mfma_i32_16x16x64_i8 v[54:57], v[166:169], v[182:185], v[54:57]
	v_mfma_i32_16x16x64_i8 v[38:41], v[162:165], v[186:189], v[38:41]
	v_mfma_i32_16x16x64_i8 v[38:41], v[166:169], v[190:193], v[38:41]
	v_mfma_i32_16x16x64_i8 v[22:25], v[162:165], v[200:203], v[22:25]
	v_mfma_i32_16x16x64_i8 v[22:25], v[166:169], v[204:207], v[22:25]
	v_mfma_i32_16x16x64_i8 v[6:9], v[162:165], v[208:211], v[6:9]
	v_mfma_i32_16x16x64_i8 v[6:9], v[166:169], v[212:215], v[6:9]
	v_mfma_i32_16x16x64_i8 v[50:53], v[170:173], v[178:181], v[50:53]
	v_mfma_i32_16x16x64_i8 v[50:53], v[174:177], v[182:185], v[50:53]
	v_mfma_i32_16x16x64_i8 v[34:37], v[170:173], v[186:189], v[34:37]
	v_mfma_i32_16x16x64_i8 v[34:37], v[174:177], v[190:193], v[34:37]
	v_mfma_i32_16x16x64_i8 v[18:21], v[170:173], v[200:203], v[18:21]
	v_mfma_i32_16x16x64_i8 v[18:21], v[174:177], v[204:207], v[18:21]
	v_mfma_i32_16x16x64_i8 v[2:5], v[170:173], v[208:211], v[2:5]
	v_mfma_i32_16x16x64_i8 v[2:5], v[174:177], v[212:215], v[2:5]
	s_barrier
	s_add_i32 s57, s57, 2
	s_add_u32 s30, s30, 0x100
	s_addc_u32 s31, s31, 0
	s_add_u32 s55, s55, 0x100
	s_addc_u32 s56, s56, 0
	s_cmp_gt_u32 s57, 29
	s_cbranch_scc0 .LBB0_779
	s_and_b64 vcc, exec, s[20:21]
	s_mov_b32 s54, 0x5c401000
	s_cbranch_vccz .LBB0_782
	s_barrier

.LBB0_801:
	s_add_u32 s34, s30, 0xfff00080
	s_addc_u32 s35, s31, -1
	s_add_i32 s54, 0, 0x10000
	s_cmp_eq_u32 s53, 60
	s_cselect_b32 s41, s25, s35
	s_cselect_b32 s40, s49, s34
	s_cselect_b32 s35, s23, s52
	s_cselect_b32 s34, s50, s51
	s_add_i32 s56, 0, 0x14000
	v_add_u32_e32 v156, s54, v141
	v_add_u32_e32 v172, s56, v141
	ds_read_b128 v[144:147], v156
	ds_read_b128 v[148:151], v156 offset:1024
	ds_read_b128 v[152:155], v156 offset:2048
	ds_read_b128 v[156:159], v156 offset:3072
	ds_read_b128 v[160:163], v172
	ds_read_b128 v[164:167], v172 offset:1024
	ds_read_b128 v[168:171], v172 offset:2048
	ds_read_b128 v[172:175], v172 offset:3072
	s_add_i32 m0, s14, 0xc000
	ds_read_b128 v[176:179], v143
	ds_read_b128 v[180:183], v143 offset:1024
	ds_read_b128 v[184:187], v143 offset:2048
	ds_read_b128 v[188:191], v143 offset:3072
	ds_read_b128 v[192:195], v143 offset:4096
	ds_read_b128 v[200:203], v143 offset:5120
	ds_read_b128 v[204:207], v143 offset:6144
	ds_read_b128 v[208:211], v143 offset:7168
	global_load_lds_dwordx4 v136, s[30:31]
	s_add_i32 m0, s14, 0xe000
	s_nop 0
	global_load_lds_dwordx4 v138, s[30:31]
	s_waitcnt vmcnt(8)
	s_waitcnt lgkmcnt(0)
	s_barrier
	s_waitcnt lgkmcnt(0)
	v_mfma_f32_16x16x32_bf16 v[126:129], v[144:147], v[176:179], v[126:129]
	v_mfma_f32_16x16x32_bf16 v[126:129], v[148:151], v[180:183], v[126:129]
	v_mfma_f32_16x16x32_bf16 v[118:121], v[144:147], v[184:187], v[118:121]
	v_mfma_f32_16x16x32_bf16 v[118:121], v[148:151], v[188:191], v[118:121]
	v_mfma_f32_16x16x32_bf16 v[102:105], v[144:147], v[192:195], v[102:105]
	v_mfma_f32_16x16x32_bf16 v[102:105], v[148:151], v[200:203], v[102:105]
	v_mfma_f32_16x16x32_bf16 v[86:89], v[144:147], v[204:207], v[86:89]
	v_mfma_f32_16x16x32_bf16 v[86:89], v[148:151], v[208:211], v[86:89]
	v_mfma_f32_16x16x32_bf16 v[122:125], v[152:155], v[176:179], v[122:125]
	v_mfma_f32_16x16x32_bf16 v[122:125], v[156:159], v[180:183], v[122:125]
	v_mfma_f32_16x16x32_bf16 v[114:117], v[152:155], v[184:187], v[114:117]
	v_mfma_f32_16x16x32_bf16 v[114:117], v[156:159], v[188:191], v[114:117]
	v_mfma_f32_16x16x32_bf16 v[98:101], v[152:155], v[192:195], v[98:101]
	v_mfma_f32_16x16x32_bf16 v[98:101], v[156:159], v[200:203], v[98:101]
	v_mfma_f32_16x16x32_bf16 v[82:85], v[152:155], v[204:207], v[82:85]
	v_mfma_f32_16x16x32_bf16 v[82:85], v[156:159], v[208:211], v[82:85]
	v_mfma_f32_16x16x32_bf16 v[110:113], v[160:163], v[176:179], v[110:113]
	v_mfma_f32_16x16x32_bf16 v[110:113], v[164:167], v[180:183], v[110:113]
	v_mfma_f32_16x16x32_bf16 v[94:97], v[160:163], v[184:187], v[94:97]
	v_mfma_f32_16x16x32_bf16 v[94:97], v[164:167], v[188:191], v[94:97]
	v_mfma_f32_16x16x32_bf16 v[78:81], v[160:163], v[192:195], v[78:81]
	v_mfma_f32_16x16x32_bf16 v[78:81], v[164:167], v[200:203], v[78:81]
	v_mfma_f32_16x16x32_bf16 v[70:73], v[160:163], v[204:207], v[70:73]
	v_mfma_f32_16x16x32_bf16 v[70:73], v[164:167], v[208:211], v[70:73]
	v_mfma_f32_16x16x32_bf16 v[106:109], v[168:171], v[176:179], v[106:109]
	v_mfma_f32_16x16x32_bf16 v[106:109], v[172:175], v[180:183], v[106:109]
	v_mfma_f32_16x16x32_bf16 v[90:93], v[168:171], v[184:187], v[90:93]
	v_mfma_f32_16x16x32_bf16 v[90:93], v[172:175], v[188:191], v[90:93]
	v_mfma_f32_16x16x32_bf16 v[74:77], v[168:171], v[192:195], v[74:77]
	v_mfma_f32_16x16x32_bf16 v[74:77], v[172:175], v[200:203], v[74:77]
	v_mfma_f32_16x16x32_bf16 v[66:69], v[168:171], v[204:207], v[66:69]
	v_mfma_f32_16x16x32_bf16 v[66:69], v[172:175], v[208:211], v[66:69]
	s_barrier
	s_add_i32 s54, s54, s9
	s_mov_b32 m0, s54
	ds_read_b128 v[176:179], v143 offset:16384
	ds_read_b128 v[180:183], v143 offset:17408
	ds_read_b128 v[184:187], v143 offset:18432
	ds_read_b128 v[188:191], v143 offset:19456
	ds_read_b128 v[192:195], v143 offset:20480
	ds_read_b128 v[200:203], v143 offset:21504
	ds_read_b128 v[204:207], v143 offset:22528
	ds_read_b128 v[208:211], v143 offset:23552
	global_load_lds_dwordx4 v0, s[34:35]
	s_add_i32 m0, s54, 0x2000
	s_add_u32 s54, s34, 0x100000
	s_addc_u32 s55, s35, 0
	s_add_i32 s56, s56, s9
	global_load_lds_dwordx4 v130, s[34:35]
	s_mov_b32 m0, s56
	s_nop 0
	global_load_lds_dwordx4 v0, s[54:55]
	s_add_i32 m0, s56, 0x2000
	s_nop 0
	global_load_lds_dwordx4 v130, s[54:55]
	s_mov_b32 m0, s14
	s_nop 0
	global_load_lds_dwordx4 v134, s[40:41]
	s_mov_b32 m0, s15
	s_nop 0
	global_load_lds_dwordx4 v132, s[40:41]
	s_waitcnt vmcnt(8)
	s_waitcnt lgkmcnt(0)
	s_barrier
	s_waitcnt lgkmcnt(0)
	v_mfma_f32_16x16x32_bf16 v[62:65], v[144:147], v[176:179], v[62:65]
	v_mfma_f32_16x16x32_bf16 v[62:65], v[148:151], v[180:183], v[62:65]
	v_mfma_f32_16x16x32_bf16 v[54:57], v[144:147], v[184:187], v[54:57]
	v_mfma_f32_16x16x32_bf16 v[54:57], v[148:151], v[188:191], v[54:57]
	v_mfma_f32_16x16x32_bf16 v[38:41], v[144:147], v[192:195], v[38:41]
	v_mfma_f32_16x16x32_bf16 v[38:41], v[148:151], v[200:203], v[38:41]
	v_mfma_f32_16x16x32_bf16 v[22:25], v[144:147], v[204:207], v[22:25]
	v_mfma_f32_16x16x32_bf16 v[22:25], v[148:151], v[208:211], v[22:25]
	v_mfma_f32_16x16x32_bf16 v[58:61], v[152:155], v[176:179], v[58:61]
	v_mfma_f32_16x16x32_bf16 v[58:61], v[156:159], v[180:183], v[58:61]
	v_mfma_f32_16x16x32_bf16 v[50:53], v[152:155], v[184:187], v[50:53]
	v_mfma_f32_16x16x32_bf16 v[50:53], v[156:159], v[188:191], v[50:53]
	v_mfma_f32_16x16x32_bf16 v[34:37], v[152:155], v[192:195], v[34:37]
	v_mfma_f32_16x16x32_bf16 v[34:37], v[156:159], v[200:203], v[34:37]
	v_mfma_f32_16x16x32_bf16 v[18:21], v[152:155], v[204:207], v[18:21]
	v_mfma_f32_16x16x32_bf16 v[18:21], v[156:159], v[208:211], v[18:21]
	v_mfma_f32_16x16x32_bf16 v[46:49], v[160:163], v[176:179], v[46:49]
	v_mfma_f32_16x16x32_bf16 v[46:49], v[164:167], v[180:183], v[46:49]
	v_mfma_f32_16x16x32_bf16 v[30:33], v[160:163], v[184:187], v[30:33]
	v_mfma_f32_16x16x32_bf16 v[30:33], v[164:167], v[188:191], v[30:33]
	v_mfma_f32_16x16x32_bf16 v[14:17], v[160:163], v[192:195], v[14:17]
	v_mfma_f32_16x16x32_bf16 v[14:17], v[164:167], v[200:203], v[14:17]
	v_mfma_f32_16x16x32_bf16 v[6:9], v[160:163], v[204:207], v[6:9]
	v_mfma_f32_16x16x32_bf16 v[6:9], v[164:167], v[208:211], v[6:9]
	v_mfma_f32_16x16x32_bf16 v[42:45], v[168:171], v[176:179], v[42:45]
	v_mfma_f32_16x16x32_bf16 v[42:45], v[172:175], v[180:183], v[42:45]
	v_mfma_f32_16x16x32_bf16 v[26:29], v[168:171], v[184:187], v[26:29]
	v_mfma_f32_16x16x32_bf16 v[26:29], v[172:175], v[188:191], v[26:29]
	v_mfma_f32_16x16x32_bf16 v[10:13], v[168:171], v[192:195], v[10:13]
	v_mfma_f32_16x16x32_bf16 v[10:13], v[172:175], v[200:203], v[10:13]
	v_mfma_f32_16x16x32_bf16 v[2:5], v[168:171], v[204:207], v[2:5]
	v_mfma_f32_16x16x32_bf16 v[2:5], v[172:175], v[208:211], v[2:5]
	s_barrier
	s_add_i32 s54, 0, 0x18000
	s_add_i32 s55, 0, 0x1c000
	v_add_u32_e32 v156, s54, v141
	v_add_u32_e32 v172, s55, v141
	ds_read_b128 v[144:147], v156
	ds_read_b128 v[148:151], v156 offset:1024
	ds_read_b128 v[152:155], v156 offset:2048
	ds_read_b128 v[156:159], v156 offset:3072
	ds_read_b128 v[160:163], v172
	ds_read_b128 v[164:167], v172 offset:1024
	ds_read_b128 v[168:171], v172 offset:2048
	ds_read_b128 v[172:175], v172 offset:3072
	s_add_u32 s40, s40, 0x100000
	s_addc_u32 s41, s41, 0
	s_mov_b32 m0, s18
	ds_read_b128 v[176:179], v143 offset:32768
	ds_read_b128 v[180:183], v143 offset:33792
	ds_read_b128 v[184:187], v143 offset:34816
	ds_read_b128 v[188:191], v143 offset:35840
	ds_read_b128 v[192:195], v143 offset:36864
	ds_read_b128 v[200:203], v143 offset:37888
	ds_read_b128 v[204:207], v143 offset:38912
	ds_read_b128 v[208:211], v143 offset:39936
	global_load_lds_dwordx4 v134, s[40:41]
	s_mov_b32 m0, s19
	s_nop 0
	global_load_lds_dwordx4 v132, s[40:41]
	s_waitcnt vmcnt(8)
	s_waitcnt lgkmcnt(0)
	s_barrier
	s_waitcnt lgkmcnt(0)
	v_mfma_f32_16x16x32_bf16 v[126:129], v[144:147], v[176:179], v[126:129]
	v_mfma_f32_16x16x32_bf16 v[126:129], v[148:151], v[180:183], v[126:129]
	v_mfma_f32_16x16x32_bf16 v[118:121], v[144:147], v[184:187], v[118:121]
	v_mfma_f32_16x16x32_bf16 v[118:121], v[148:151], v[188:191], v[118:121]
	v_mfma_f32_16x16x32_bf16 v[102:105], v[144:147], v[192:195], v[102:105]
	v_mfma_f32_16x16x32_bf16 v[102:105], v[148:151], v[200:203], v[102:105]
	v_mfma_f32_16x16x32_bf16 v[86:89], v[144:147], v[204:207], v[86:89]
	v_mfma_f32_16x16x32_bf16 v[86:89], v[148:151], v[208:211], v[86:89]
	v_mfma_f32_16x16x32_bf16 v[122:125], v[152:155], v[176:179], v[122:125]
	v_mfma_f32_16x16x32_bf16 v[122:125], v[156:159], v[180:183], v[122:125]
	v_mfma_f32_16x16x32_bf16 v[114:117], v[152:155], v[184:187], v[114:117]
	v_mfma_f32_16x16x32_bf16 v[114:117], v[156:159], v[188:191], v[114:117]
	v_mfma_f32_16x16x32_bf16 v[98:101], v[152:155], v[192:195], v[98:101]
	v_mfma_f32_16x16x32_bf16 v[98:101], v[156:159], v[200:203], v[98:101]
	v_mfma_f32_16x16x32_bf16 v[82:85], v[152:155], v[204:207], v[82:85]
	v_mfma_f32_16x16x32_bf16 v[82:85], v[156:159], v[208:211], v[82:85]
	v_mfma_f32_16x16x32_bf16 v[110:113], v[160:163], v[176:179], v[110:113]
	v_mfma_f32_16x16x32_bf16 v[110:113], v[164:167], v[180:183], v[110:113]
	v_mfma_f32_16x16x32_bf16 v[94:97], v[160:163], v[184:187], v[94:97]
	v_mfma_f32_16x16x32_bf16 v[94:97], v[164:167], v[188:191], v[94:97]
	v_mfma_f32_16x16x32_bf16 v[78:81], v[160:163], v[192:195], v[78:81]
	v_mfma_f32_16x16x32_bf16 v[78:81], v[164:167], v[200:203], v[78:81]
	v_mfma_f32_16x16x32_bf16 v[70:73], v[160:163], v[204:207], v[70:73]
	v_mfma_f32_16x16x32_bf16 v[70:73], v[164:167], v[208:211], v[70:73]
	v_mfma_f32_16x16x32_bf16 v[106:109], v[168:171], v[176:179], v[106:109]
	v_mfma_f32_16x16x32_bf16 v[106:109], v[172:175], v[180:183], v[106:109]
	v_mfma_f32_16x16x32_bf16 v[90:93], v[168:171], v[184:187], v[90:93]
	v_mfma_f32_16x16x32_bf16 v[90:93], v[172:175], v[188:191], v[90:93]
	v_mfma_f32_16x16x32_bf16 v[74:77], v[168:171], v[192:195], v[74:77]
	v_mfma_f32_16x16x32_bf16 v[74:77], v[172:175], v[200:203], v[74:77]
	v_mfma_f32_16x16x32_bf16 v[66:69], v[168:171], v[204:207], v[66:69]
	v_mfma_f32_16x16x32_bf16 v[66:69], v[172:175], v[208:211], v[66:69]
	s_barrier
	s_add_u32 s100, s40, 0xfff00080
	s_addc_u32 s101, s41, -1
	s_add_u32 s98, s34, 0x80
	s_addc_u32 s99, s35, 0
	s_add_i32 s40, s54, s9
	s_mov_b32 m0, s40
	ds_read_b128 v[176:179], v143 offset:49152
	ds_read_b128 v[180:183], v143 offset:50176
	ds_read_b128 v[184:187], v143 offset:51200
	ds_read_b128 v[188:191], v143 offset:52224
	ds_read_b128 v[192:195], v143 offset:53248
	ds_read_b128 v[200:203], v143 offset:54272
	ds_read_b128 v[204:207], v143 offset:55296
	ds_read_b128 v[208:211], v143 offset:56320
	global_load_lds_dwordx4 v0, s[98:99]
	s_add_i32 m0, s40, 0x2000
	s_add_u32 s34, s34, 0x100080
	s_addc_u32 s35, s35, 0
	s_add_i32 s40, s55, s9
	global_load_lds_dwordx4 v130, s[98:99]
	s_mov_b32 m0, s40
	s_nop 0
	global_load_lds_dwordx4 v0, s[34:35]
	s_add_i32 m0, s40, 0x2000
	s_nop 0
	global_load_lds_dwordx4 v130, s[34:35]
	s_mov_b32 m0, s42
	s_nop 0
	global_load_lds_dwordx4 v134, s[100:101]
	s_mov_b32 m0, s43
	s_nop 0
	global_load_lds_dwordx4 v132, s[100:101]
	s_waitcnt vmcnt(8)
	s_waitcnt lgkmcnt(0)
	s_barrier
	s_waitcnt lgkmcnt(0)
	v_mfma_f32_16x16x32_bf16 v[62:65], v[144:147], v[176:179], v[62:65]
	v_mfma_f32_16x16x32_bf16 v[62:65], v[148:151], v[180:183], v[62:65]
	v_mfma_f32_16x16x32_bf16 v[54:57], v[144:147], v[184:187], v[54:57]
	v_mfma_f32_16x16x32_bf16 v[54:57], v[148:151], v[188:191], v[54:57]
	v_mfma_f32_16x16x32_bf16 v[38:41], v[144:147], v[192:195], v[38:41]
	v_mfma_f32_16x16x32_bf16 v[38:41], v[148:151], v[200:203], v[38:41]
	v_mfma_f32_16x16x32_bf16 v[22:25], v[144:147], v[204:207], v[22:25]
	v_mfma_f32_16x16x32_bf16 v[22:25], v[148:151], v[208:211], v[22:25]
	v_mfma_f32_16x16x32_bf16 v[58:61], v[152:155], v[176:179], v[58:61]
	v_mfma_f32_16x16x32_bf16 v[58:61], v[156:159], v[180:183], v[58:61]
	v_mfma_f32_16x16x32_bf16 v[50:53], v[152:155], v[184:187], v[50:53]
	v_mfma_f32_16x16x32_bf16 v[50:53], v[156:159], v[188:191], v[50:53]
	v_mfma_f32_16x16x32_bf16 v[34:37], v[152:155], v[192:195], v[34:37]
	v_mfma_f32_16x16x32_bf16 v[34:37], v[156:159], v[200:203], v[34:37]
	v_mfma_f32_16x16x32_bf16 v[18:21], v[152:155], v[204:207], v[18:21]
	v_mfma_f32_16x16x32_bf16 v[18:21], v[156:159], v[208:211], v[18:21]
	v_mfma_f32_16x16x32_bf16 v[46:49], v[160:163], v[176:179], v[46:49]
	v_mfma_f32_16x16x32_bf16 v[46:49], v[164:167], v[180:183], v[46:49]
	v_mfma_f32_16x16x32_bf16 v[30:33], v[160:163], v[184:187], v[30:33]
	v_mfma_f32_16x16x32_bf16 v[30:33], v[164:167], v[188:191], v[30:33]
	v_mfma_f32_16x16x32_bf16 v[14:17], v[160:163], v[192:195], v[14:17]
	v_mfma_f32_16x16x32_bf16 v[14:17], v[164:167], v[200:203], v[14:17]
	v_mfma_f32_16x16x32_bf16 v[6:9], v[160:163], v[204:207], v[6:9]
	v_mfma_f32_16x16x32_bf16 v[6:9], v[164:167], v[208:211], v[6:9]
	v_mfma_f32_16x16x32_bf16 v[42:45], v[168:171], v[176:179], v[42:45]
	v_mfma_f32_16x16x32_bf16 v[42:45], v[172:175], v[180:183], v[42:45]
	v_mfma_f32_16x16x32_bf16 v[26:29], v[168:171], v[184:187], v[26:29]
	v_mfma_f32_16x16x32_bf16 v[26:29], v[172:175], v[188:191], v[26:29]
	v_mfma_f32_16x16x32_bf16 v[10:13], v[168:171], v[192:195], v[10:13]
	v_mfma_f32_16x16x32_bf16 v[10:13], v[172:175], v[200:203], v[10:13]
	v_mfma_f32_16x16x32_bf16 v[2:5], v[168:171], v[204:207], v[2:5]
	v_mfma_f32_16x16x32_bf16 v[2:5], v[172:175], v[208:211], v[2:5]
	s_barrier
	s_add_i32 s53, s53, 2
	s_add_u32 s30, s30, 0x100
	s_addc_u32 s31, s31, 0
	s_add_u32 s51, s51, 0x100
	s_addc_u32 s52, s52, 0
	s_cmp_gt_u32 s53, 61
	s_cbranch_scc0 .LBB0_801
	s_and_b64 vcc, exec, s[20:21]
	s_cbranch_vccz .LBB0_804
	s_barrier
